# phase0: X copy 16 loads in flight, silu staging unrolled, adaLN GEMV 32 loads in flight per wave
# speedup vs baseline: 1.0047x; 1.0047x over previous
.LBB0_7:
	s_or_b64 exec, exec, s[24:25]
	v_mov_b32_e32 v2, v179
	s_mov_b32 s37, 0
	s_lshl_b64 s[24:25], s[36:37], 9
	v_ashrrev_i32_e32 v3, 31, v2
	v_lshl_add_u64 v[4:5], s[24:25], 0, v[2:3]
	s_add_i32 s24, 0, 0x27fe0
	v_mov_b32_e32 v1, s24
	s_add_i32 s24, 0, 0x27fe4
	v_mov_b32_e32 v6, s24
	ds_read_b32 v1, v1
	ds_read_b32 v6, v6
	s_load_dwordx16 s[48:63], s[0:1], 0x0
	s_mov_b32 s34, s20
	s_mov_b32 s35, s37
	s_mov_b64 s[28:29], 0x880000
	s_lshl_b64 s[24:25], s[34:35], 9
	s_waitcnt lgkmcnt(0)
	v_readfirstlane_b32 s26, v1
	v_readfirstlane_b32 s27, v6
	s_cmp_lg_u32 s20, 0x100
	s_cbranch_scc1 .Lxcopy_generic
	v_lshlrev_b32_e32 v6, 4, v4
	s_mov_b64 s[30:31], s[48:49]
	s_mov_b64 s[38:39], s[26:27]
	s_mov_b32 s33, 4
.Lxcopy_x:
	global_load_dwordx4 v[112:115], v6, s[30:31]
	s_add_u32 s30, s30, 0x200000
	s_addc_u32 s31, s31, 0
	global_load_dwordx4 v[116:119], v6, s[30:31]
	s_add_u32 s30, s30, 0x200000
	s_addc_u32 s31, s31, 0
	global_load_dwordx4 v[120:123], v6, s[30:31]
	s_add_u32 s30, s30, 0x200000
	s_addc_u32 s31, s31, 0
	global_load_dwordx4 v[124:127], v6, s[30:31]
	s_add_u32 s30, s30, 0x200000
	s_addc_u32 s31, s31, 0
	global_load_dwordx4 v[128:131], v6, s[30:31]
	s_add_u32 s30, s30, 0x200000
	s_addc_u32 s31, s31, 0
	global_load_dwordx4 v[132:135], v6, s[30:31]
	s_add_u32 s30, s30, 0x200000
	s_addc_u32 s31, s31, 0
	global_load_dwordx4 v[136:139], v6, s[30:31]
	s_add_u32 s30, s30, 0x200000
	s_addc_u32 s31, s31, 0
	global_load_dwordx4 v[140:143], v6, s[30:31]
	s_add_u32 s30, s30, 0x200000
	s_addc_u32 s31, s31, 0
	global_load_dwordx4 v[144:147], v6, s[30:31]
	s_add_u32 s30, s30, 0x200000
	s_addc_u32 s31, s31, 0
	global_load_dwordx4 v[148:151], v6, s[30:31]
	s_add_u32 s30, s30, 0x200000
	s_addc_u32 s31, s31, 0
	global_load_dwordx4 v[152:155], v6, s[30:31]
	s_add_u32 s30, s30, 0x200000
	s_addc_u32 s31, s31, 0
	global_load_dwordx4 v[156:159], v6, s[30:31]
	s_add_u32 s30, s30, 0x200000
	s_addc_u32 s31, s31, 0
	global_load_dwordx4 v[160:163], v6, s[30:31]
	s_add_u32 s30, s30, 0x200000
	s_addc_u32 s31, s31, 0
	global_load_dwordx4 v[164:167], v6, s[30:31]
	s_add_u32 s30, s30, 0x200000
	s_addc_u32 s31, s31, 0
	global_load_dwordx4 v[168:171], v6, s[30:31]
	s_add_u32 s30, s30, 0x200000
	s_addc_u32 s31, s31, 0
	global_load_dwordx4 v[172:175], v6, s[30:31]
	s_add_u32 s30, s30, 0x200000
	s_addc_u32 s31, s31, 0
	s_waitcnt vmcnt(0)
	global_store_dwordx4 v6, v[112:115], s[38:39]
	s_add_u32 s38, s38, 0x200000
	s_addc_u32 s39, s39, 0
	global_store_dwordx4 v6, v[116:119], s[38:39]
	s_add_u32 s38, s38, 0x200000
	s_addc_u32 s39, s39, 0
	global_store_dwordx4 v6, v[120:123], s[38:39]
	s_add_u32 s38, s38, 0x200000
	s_addc_u32 s39, s39, 0
	global_store_dwordx4 v6, v[124:127], s[38:39]
	s_add_u32 s38, s38, 0x200000
	s_addc_u32 s39, s39, 0
	global_store_dwordx4 v6, v[128:131], s[38:39]
	s_add_u32 s38, s38, 0x200000
	s_addc_u32 s39, s39, 0
	global_store_dwordx4 v6, v[132:135], s[38:39]
	s_add_u32 s38, s38, 0x200000
	s_addc_u32 s39, s39, 0
	global_store_dwordx4 v6, v[136:139], s[38:39]
	s_add_u32 s38, s38, 0x200000
	s_addc_u32 s39, s39, 0
	global_store_dwordx4 v6, v[140:143], s[38:39]
	s_add_u32 s38, s38, 0x200000
	s_addc_u32 s39, s39, 0
	global_store_dwordx4 v6, v[144:147], s[38:39]
	s_add_u32 s38, s38, 0x200000
	s_addc_u32 s39, s39, 0
	global_store_dwordx4 v6, v[148:151], s[38:39]
	s_add_u32 s38, s38, 0x200000
	s_addc_u32 s39, s39, 0
	global_store_dwordx4 v6, v[152:155], s[38:39]
	s_add_u32 s38, s38, 0x200000
	s_addc_u32 s39, s39, 0
	global_store_dwordx4 v6, v[156:159], s[38:39]
	s_add_u32 s38, s38, 0x200000
	s_addc_u32 s39, s39, 0
	global_store_dwordx4 v6, v[160:163], s[38:39]
	s_add_u32 s38, s38, 0x200000
	s_addc_u32 s39, s39, 0
	global_store_dwordx4 v6, v[164:167], s[38:39]
	s_add_u32 s38, s38, 0x200000
	s_addc_u32 s39, s39, 0
	global_store_dwordx4 v6, v[168:171], s[38:39]
	s_add_u32 s38, s38, 0x200000
	s_addc_u32 s39, s39, 0
	global_store_dwordx4 v6, v[172:175], s[38:39]
	s_add_u32 s38, s38, 0x200000
	s_addc_u32 s39, s39, 0
	s_add_i32 s33, s33, -1
	s_cmp_lg_u32 s33, 0
	s_cbranch_scc1 .Lxcopy_x
	s_mov_b64 s[30:31], s[52:53]
	global_load_dwordx4 v[112:115], v6, s[30:31]
	s_add_u32 s30, s30, 0x200000
	s_addc_u32 s31, s31, 0
	global_load_dwordx4 v[116:119], v6, s[30:31]
	s_add_u32 s30, s30, 0x200000
	s_addc_u32 s31, s31, 0
	global_load_dwordx4 v[120:123], v6, s[30:31]
	s_add_u32 s30, s30, 0x200000
	s_addc_u32 s31, s31, 0
	global_load_dwordx4 v[124:127], v6, s[30:31]
	s_add_u32 s30, s30, 0x200000
	s_addc_u32 s31, s31, 0
	s_waitcnt vmcnt(0)
	global_store_dwordx4 v6, v[112:115], s[38:39]
	s_add_u32 s38, s38, 0x200000
	s_addc_u32 s39, s39, 0
	global_store_dwordx4 v6, v[116:119], s[38:39]
	s_add_u32 s38, s38, 0x200000
	s_addc_u32 s39, s39, 0
	global_store_dwordx4 v6, v[120:123], s[38:39]
	s_add_u32 s38, s38, 0x200000
	s_addc_u32 s39, s39, 0
	global_store_dwordx4 v6, v[124:127], s[38:39]
	s_add_u32 s38, s38, 0x200000
	s_addc_u32 s39, s39, 0
	s_branch .Lxcopy_done
.Lxcopy_generic:
	v_cmp_gt_u64_e32 vcc, s[28:29], v[4:5]
	s_and_saveexec_b64 s[28:29], vcc
	s_cbranch_execz .LBB0_10
	s_add_u32 s30, s52, 0xf8000000
	s_addc_u32 s31, s53, -1
	s_lshl_b64 s[38:39], s[36:37], 13
	v_lshl_add_u64 v[6:7], v[2:3], 4, s[38:39]
	s_lshl_b64 s[34:35], s[34:35], 13
	s_mov_b64 s[38:39], 0
	s_mov_b64 s[40:41], 0x800000
	s_mov_b64 s[42:43], 0x87ffff
	v_mov_b64_e32 v[8:9], v[4:5]

.Lxcopy_done:
	s_load_dwordx16 s[64:79], s[0:1], 0x40
	s_add_i32 s0, 0, 0x27fe0
	v_mov_b32_e32 v1, s0
	s_add_i32 s0, 0, 0x27fe4
	v_mov_b32_e32 v6, s0
	s_waitcnt lgkmcnt(0)
	v_writelane_b32 v250, s64, 0
	ds_read_b32 v1, v1
	ds_read_b32 v6, v6
	v_writelane_b32 v250, s65, 1
	v_writelane_b32 v250, s66, 2
	v_writelane_b32 v250, s67, 3
	v_writelane_b32 v250, s68, 4
	v_writelane_b32 v250, s69, 5
	v_writelane_b32 v250, s70, 6
	v_writelane_b32 v250, s71, 7
	v_writelane_b32 v250, s72, 8
	v_writelane_b32 v250, s73, 9
	v_writelane_b32 v250, s74, 10
	v_writelane_b32 v250, s75, 11
	v_writelane_b32 v250, s76, 12
	v_writelane_b32 v250, s77, 13
	v_writelane_b32 v250, s78, 14
	s_mov_b64 s[0:1], 0x200000
	v_writelane_b32 v250, s79, 15
	s_waitcnt lgkmcnt(0)
	v_readfirstlane_b32 s26, v1
	v_readfirstlane_b32 s27, v6
	v_cmp_gt_u64_e32 vcc, s[0:1], v[4:5]
	s_and_saveexec_b64 s[0:1], vcc
	s_cbranch_execz .LBB0_45
	s_add_u32 s26, s26, 0x8944000
	v_lshlrev_b32_e32 v1, 3, v2
	s_addc_u32 s27, s27, 0
	v_lshl_add_u32 v1, s36, 12, v1
	s_lshl_b32 s33, s20, 12
	s_mov_b64 s[28:29], 0
	s_movk_i32 s37, 0x800
	s_movk_i32 s38, 0x801
	s_mov_b32 s39, 0x7f800000
	v_mov_b32_e32 v8, 0xbf1f24be
	v_mov_b32_e32 v9, 0x3e642e9d
	s_brev_b32 s40, 1
	v_mov_b32_e32 v7, 0
	s_mov_b64 s[30:31], 0x1fffff
	v_mov_b32_e32 v10, 0x7fc00000
	s_branch .LBB0_13

.LBB0_45:
	s_or_b64 exec, exec, s[0:1]
	s_mov_b64 s[0:1], exec
	v_lshlrev_b32_e32 v1, 2, v2
	s_mov_b64 s[24:25], s[50:51]
	global_load_dword v112, v1, s[24:25]
	s_add_u32 s24, s24, 0x800
	s_addc_u32 s25, s25, 0
	global_load_dword v113, v1, s[24:25]
	s_add_u32 s24, s24, 0x800
	s_addc_u32 s25, s25, 0
	global_load_dword v114, v1, s[24:25]
	s_add_u32 s24, s24, 0x800
	s_addc_u32 s25, s25, 0
	global_load_dword v115, v1, s[24:25]
	s_add_u32 s24, s24, 0x800
	s_addc_u32 s25, s25, 0
	global_load_dword v116, v1, s[24:25]
	s_add_u32 s24, s24, 0x800
	s_addc_u32 s25, s25, 0
	global_load_dword v117, v1, s[24:25]
	s_add_u32 s24, s24, 0x800
	s_addc_u32 s25, s25, 0
	global_load_dword v118, v1, s[24:25]
	s_add_u32 s24, s24, 0x800
	s_addc_u32 s25, s25, 0
	global_load_dword v119, v1, s[24:25]
	s_add_u32 s24, s24, 0x800
	s_addc_u32 s25, s25, 0
	global_load_dword v120, v1, s[24:25]
	s_add_u32 s24, s24, 0x800
	s_addc_u32 s25, s25, 0
	global_load_dword v121, v1, s[24:25]
	s_add_u32 s24, s24, 0x800
	s_addc_u32 s25, s25, 0
	global_load_dword v122, v1, s[24:25]
	s_add_u32 s24, s24, 0x800
	s_addc_u32 s25, s25, 0
	global_load_dword v123, v1, s[24:25]
	s_add_u32 s24, s24, 0x800
	s_addc_u32 s25, s25, 0
	global_load_dword v124, v1, s[24:25]
	s_add_u32 s24, s24, 0x800
	s_addc_u32 s25, s25, 0
	global_load_dword v125, v1, s[24:25]
	s_add_u32 s24, s24, 0x800
	s_addc_u32 s25, s25, 0
	global_load_dword v126, v1, s[24:25]
	s_add_u32 s24, s24, 0x800
	s_addc_u32 s25, s25, 0
	global_load_dword v127, v1, s[24:25]
	s_add_u32 s24, s24, 0x800
	s_addc_u32 s25, s25, 0
	s_mov_b64 s[24:25], s[54:55]
	global_load_dword v128, v1, s[24:25]
	global_load_dword v129, v1, s[24:25] offset:2048
	s_waitcnt vmcnt(0)
	v_mul_f32_e32 v130, 0xbfb8aa3b, v112
	v_mul_f32_e32 v131, 0xbfb8aa3b, v113
	v_mul_f32_e32 v132, 0xbfb8aa3b, v114
	v_mul_f32_e32 v133, 0xbfb8aa3b, v115
	v_mul_f32_e32 v134, 0xbfb8aa3b, v116
	v_mul_f32_e32 v135, 0xbfb8aa3b, v117
	v_mul_f32_e32 v136, 0xbfb8aa3b, v118
	v_mul_f32_e32 v137, 0xbfb8aa3b, v119
	v_mul_f32_e32 v138, 0xbfb8aa3b, v120
	v_mul_f32_e32 v139, 0xbfb8aa3b, v121
	v_mul_f32_e32 v140, 0xbfb8aa3b, v122
	v_mul_f32_e32 v141, 0xbfb8aa3b, v123
	v_mul_f32_e32 v142, 0xbfb8aa3b, v124
	v_mul_f32_e32 v143, 0xbfb8aa3b, v125
	v_mul_f32_e32 v144, 0xbfb8aa3b, v126
	v_mul_f32_e32 v145, 0xbfb8aa3b, v127
	v_mul_f32_e32 v146, 0xbfb8aa3b, v128
	v_mul_f32_e32 v147, 0xbfb8aa3b, v129
	v_exp_f32_e32 v130, v130
	v_exp_f32_e32 v131, v131
	v_exp_f32_e32 v132, v132
	v_exp_f32_e32 v133, v133
	v_exp_f32_e32 v134, v134
	v_exp_f32_e32 v135, v135
	v_exp_f32_e32 v136, v136
	v_exp_f32_e32 v137, v137
	v_exp_f32_e32 v138, v138
	v_exp_f32_e32 v139, v139
	v_exp_f32_e32 v140, v140
	v_exp_f32_e32 v141, v141
	v_exp_f32_e32 v142, v142
	v_exp_f32_e32 v143, v143
	v_exp_f32_e32 v144, v144
	v_exp_f32_e32 v145, v145
	v_exp_f32_e32 v146, v146
	v_exp_f32_e32 v147, v147
	v_add_f32_e32 v130, 1.0, v130
	v_add_f32_e32 v131, 1.0, v131
	v_add_f32_e32 v132, 1.0, v132
	v_add_f32_e32 v133, 1.0, v133
	v_add_f32_e32 v134, 1.0, v134
	v_add_f32_e32 v135, 1.0, v135
	v_add_f32_e32 v136, 1.0, v136
	v_add_f32_e32 v137, 1.0, v137
	v_add_f32_e32 v138, 1.0, v138
	v_add_f32_e32 v139, 1.0, v139
	v_add_f32_e32 v140, 1.0, v140
	v_add_f32_e32 v141, 1.0, v141
	v_add_f32_e32 v142, 1.0, v142
	v_add_f32_e32 v143, 1.0, v143
	v_add_f32_e32 v144, 1.0, v144
	v_add_f32_e32 v145, 1.0, v145
	v_add_f32_e32 v146, 1.0, v146
	v_add_f32_e32 v147, 1.0, v147
	v_rcp_f32_e32 v130, v130
	v_rcp_f32_e32 v131, v131
	v_rcp_f32_e32 v132, v132
	v_rcp_f32_e32 v133, v133
	v_rcp_f32_e32 v134, v134
	v_rcp_f32_e32 v135, v135
	v_rcp_f32_e32 v136, v136
	v_rcp_f32_e32 v137, v137
	v_rcp_f32_e32 v138, v138
	v_rcp_f32_e32 v139, v139
	v_rcp_f32_e32 v140, v140
	v_rcp_f32_e32 v141, v141
	v_rcp_f32_e32 v142, v142
	v_rcp_f32_e32 v143, v143
	v_rcp_f32_e32 v144, v144
	v_rcp_f32_e32 v145, v145
	v_rcp_f32_e32 v146, v146
	v_rcp_f32_e32 v147, v147
	v_mul_f32_e32 v112, v112, v130
	v_mul_f32_e32 v113, v113, v131
	v_mul_f32_e32 v114, v114, v132
	v_mul_f32_e32 v115, v115, v133
	v_mul_f32_e32 v116, v116, v134
	v_mul_f32_e32 v117, v117, v135
	v_mul_f32_e32 v118, v118, v136
	v_mul_f32_e32 v119, v119, v137
	v_mul_f32_e32 v120, v120, v138
	v_mul_f32_e32 v121, v121, v139
	v_mul_f32_e32 v122, v122, v140
	v_mul_f32_e32 v123, v123, v141
	v_mul_f32_e32 v124, v124, v142
	v_mul_f32_e32 v125, v125, v143
	v_mul_f32_e32 v126, v126, v144
	v_mul_f32_e32 v127, v127, v145
	v_mul_f32_e32 v128, v128, v146
	v_mul_f32_e32 v129, v129, v147
	ds_write_b32 v1, v112
	ds_write_b32 v1, v113 offset:2048
	ds_write_b32 v1, v114 offset:4096
	ds_write_b32 v1, v115 offset:6144
	ds_write_b32 v1, v116 offset:8192
	ds_write_b32 v1, v117 offset:10240
	ds_write_b32 v1, v118 offset:12288
	ds_write_b32 v1, v119 offset:14336
	ds_write_b32 v1, v120 offset:16384
	ds_write_b32 v1, v121 offset:18432
	ds_write_b32 v1, v122 offset:20480
	ds_write_b32 v1, v123 offset:22528
	ds_write_b32 v1, v124 offset:24576
	ds_write_b32 v1, v125 offset:26624
	ds_write_b32 v1, v126 offset:28672
	ds_write_b32 v1, v127 offset:30720
	ds_write_b32 v1, v128 offset:32768
	ds_write_b32 v1, v129 offset:34816

.LBB0_51:
	s_mul_hi_i32 s0, s37, 0x38e38e39
	s_lshr_b32 s1, s0, 31
	s_ashr_i32 s0, s0, 5
	s_add_i32 s26, s0, s1
	s_mul_i32 s0, s26, 0x2400
	s_sub_i32 s0, s31, s0
	s_ashr_i32 s1, s0, 31
	s_mul_i32 s25, s26, 0x2400000
	s_lshl_b64 s[0:1], s[0:1], 2
	s_mul_hi_i32 s24, s26, 0x2400000
	s_add_u32 s0, s25, s0
	s_addc_u32 s1, s24, s1
	v_lshl_add_u64 v[10:11], v[8:9], 0, s[0:1]
	s_mov_b64 s[24:25], 0
	v_mov_b32_e32 v21, v3
	v_mov_b32_e32 v12, 0
	v_mov_b32_e32 v13, v5
	v_mov_b32_e32 v14, 0
	v_mov_b32_e32 v15, v5
	v_mov_b32_e32 v16, 0
	v_mov_b32_e32 v17, v5
	v_mov_b32_e32 v18, 0
	v_mov_b32_e32 v19, v5
	v_mov_b32_e32 v22, 0
	s_mov_b32 s0, 0x9000
	s_mov_b32 s1, 0
.Lgemv_blk:
	v_lshl_add_u64 v[24:25], v[10:11], 0, s[24:25]
	global_load_dword v112, v[24:25], off
	v_lshl_add_u64 v[24:25], v[24:25], 0, s[0:1]
	global_load_dword v113, v[24:25], off
	v_lshl_add_u64 v[24:25], v[24:25], 0, s[0:1]
	global_load_dword v114, v[24:25], off
	v_lshl_add_u64 v[24:25], v[24:25], 0, s[0:1]
	global_load_dword v115, v[24:25], off
	v_lshl_add_u64 v[24:25], v[24:25], 0, s[0:1]
	global_load_dword v116, v[24:25], off
	v_lshl_add_u64 v[24:25], v[24:25], 0, s[0:1]
	global_load_dword v117, v[24:25], off
	v_lshl_add_u64 v[24:25], v[24:25], 0, s[0:1]
	global_load_dword v118, v[24:25], off
	v_lshl_add_u64 v[24:25], v[24:25], 0, s[0:1]
	global_load_dword v119, v[24:25], off
	v_lshl_add_u64 v[24:25], v[24:25], 0, s[0:1]
	global_load_dword v120, v[24:25], off
	v_lshl_add_u64 v[24:25], v[24:25], 0, s[0:1]
	global_load_dword v121, v[24:25], off
	v_lshl_add_u64 v[24:25], v[24:25], 0, s[0:1]
	global_load_dword v122, v[24:25], off
	v_lshl_add_u64 v[24:25], v[24:25], 0, s[0:1]
	global_load_dword v123, v[24:25], off
	v_lshl_add_u64 v[24:25], v[24:25], 0, s[0:1]
	global_load_dword v124, v[24:25], off
	v_lshl_add_u64 v[24:25], v[24:25], 0, s[0:1]
	global_load_dword v125, v[24:25], off
	v_lshl_add_u64 v[24:25], v[24:25], 0, s[0:1]
	global_load_dword v126, v[24:25], off
	v_lshl_add_u64 v[24:25], v[24:25], 0, s[0:1]
	global_load_dword v127, v[24:25], off
	v_lshl_add_u64 v[24:25], v[24:25], 0, s[0:1]
	global_load_dword v128, v[24:25], off
	v_lshl_add_u64 v[24:25], v[24:25], 0, s[0:1]
	global_load_dword v129, v[24:25], off
	v_lshl_add_u64 v[24:25], v[24:25], 0, s[0:1]
	global_load_dword v130, v[24:25], off
	v_lshl_add_u64 v[24:25], v[24:25], 0, s[0:1]
	global_load_dword v131, v[24:25], off
	v_lshl_add_u64 v[24:25], v[24:25], 0, s[0:1]
	global_load_dword v132, v[24:25], off
	v_lshl_add_u64 v[24:25], v[24:25], 0, s[0:1]
	global_load_dword v133, v[24:25], off
	v_lshl_add_u64 v[24:25], v[24:25], 0, s[0:1]
	global_load_dword v134, v[24:25], off
	v_lshl_add_u64 v[24:25], v[24:25], 0, s[0:1]
	global_load_dword v135, v[24:25], off
	v_lshl_add_u64 v[24:25], v[24:25], 0, s[0:1]
	global_load_dword v136, v[24:25], off
	v_lshl_add_u64 v[24:25], v[24:25], 0, s[0:1]
	global_load_dword v137, v[24:25], off
	v_lshl_add_u64 v[24:25], v[24:25], 0, s[0:1]
	global_load_dword v138, v[24:25], off
	v_lshl_add_u64 v[24:25], v[24:25], 0, s[0:1]
	global_load_dword v139, v[24:25], off
	v_lshl_add_u64 v[24:25], v[24:25], 0, s[0:1]
	global_load_dword v140, v[24:25], off
	v_lshl_add_u64 v[24:25], v[24:25], 0, s[0:1]
	global_load_dword v141, v[24:25], off
	v_lshl_add_u64 v[24:25], v[24:25], 0, s[0:1]
	global_load_dword v142, v[24:25], off
	v_lshl_add_u64 v[24:25], v[24:25], 0, s[0:1]
	global_load_dword v143, v[24:25], off
	ds_read_b128 v[24:27], v21
	ds_read_b128 v[28:31], v21 offset:4096
	ds_read_b128 v[32:35], v21 offset:8192
	ds_read_b128 v[36:39], v21 offset:12288
	ds_read_b128 v[40:43], v21 offset:16384
	ds_read_b128 v[44:47], v21 offset:20480
	ds_read_b128 v[48:51], v21 offset:24576
	ds_read_b128 v[52:55], v21 offset:28672
	ds_read_b128 v[56:59], v21 offset:32768
	s_waitcnt vmcnt(28) lgkmcnt(0)
	v_fmac_f32_e32 v12, v112, v24
	v_fmac_f32_e32 v13, v112, v28
	v_fmac_f32_e32 v14, v112, v32
	v_fmac_f32_e32 v15, v112, v36
	v_fmac_f32_e32 v16, v112, v40
	v_fmac_f32_e32 v17, v112, v44
	v_fmac_f32_e32 v18, v112, v48
	v_fmac_f32_e32 v19, v112, v52
	v_fmac_f32_e32 v22, v112, v56
	v_fmac_f32_e32 v12, v113, v25
	v_fmac_f32_e32 v13, v113, v29
	v_fmac_f32_e32 v14, v113, v33
	v_fmac_f32_e32 v15, v113, v37
	v_fmac_f32_e32 v16, v113, v41
	v_fmac_f32_e32 v17, v113, v45
	v_fmac_f32_e32 v18, v113, v49
	v_fmac_f32_e32 v19, v113, v53
	v_fmac_f32_e32 v22, v113, v57
	v_fmac_f32_e32 v12, v114, v26
	v_fmac_f32_e32 v13, v114, v30
	v_fmac_f32_e32 v14, v114, v34
	v_fmac_f32_e32 v15, v114, v38
	v_fmac_f32_e32 v16, v114, v42
	v_fmac_f32_e32 v17, v114, v46
	v_fmac_f32_e32 v18, v114, v50
	v_fmac_f32_e32 v19, v114, v54
	v_fmac_f32_e32 v22, v114, v58
	v_fmac_f32_e32 v12, v115, v27
	v_fmac_f32_e32 v13, v115, v31
	v_fmac_f32_e32 v14, v115, v35
	v_fmac_f32_e32 v15, v115, v39
	v_fmac_f32_e32 v16, v115, v43
	v_fmac_f32_e32 v17, v115, v47
	v_fmac_f32_e32 v18, v115, v51
	v_fmac_f32_e32 v19, v115, v55
	v_fmac_f32_e32 v22, v115, v59
	ds_read_b128 v[24:27], v21 offset:16
	ds_read_b128 v[28:31], v21 offset:4112
	ds_read_b128 v[32:35], v21 offset:8208
	ds_read_b128 v[36:39], v21 offset:12304
	ds_read_b128 v[40:43], v21 offset:16400
	ds_read_b128 v[44:47], v21 offset:20496
	ds_read_b128 v[48:51], v21 offset:24592
	ds_read_b128 v[52:55], v21 offset:28688
	ds_read_b128 v[56:59], v21 offset:32784
	s_waitcnt vmcnt(24) lgkmcnt(0)
	v_fmac_f32_e32 v12, v116, v24
	v_fmac_f32_e32 v13, v116, v28
	v_fmac_f32_e32 v14, v116, v32
	v_fmac_f32_e32 v15, v116, v36
	v_fmac_f32_e32 v16, v116, v40
	v_fmac_f32_e32 v17, v116, v44
	v_fmac_f32_e32 v18, v116, v48
	v_fmac_f32_e32 v19, v116, v52
	v_fmac_f32_e32 v22, v116, v56
	v_fmac_f32_e32 v12, v117, v25
	v_fmac_f32_e32 v13, v117, v29
	v_fmac_f32_e32 v14, v117, v33
	v_fmac_f32_e32 v15, v117, v37
	v_fmac_f32_e32 v16, v117, v41
	v_fmac_f32_e32 v17, v117, v45
	v_fmac_f32_e32 v18, v117, v49
	v_fmac_f32_e32 v19, v117, v53
	v_fmac_f32_e32 v22, v117, v57
	v_fmac_f32_e32 v12, v118, v26
	v_fmac_f32_e32 v13, v118, v30
	v_fmac_f32_e32 v14, v118, v34
	v_fmac_f32_e32 v15, v118, v38
	v_fmac_f32_e32 v16, v118, v42
	v_fmac_f32_e32 v17, v118, v46
	v_fmac_f32_e32 v18, v118, v50
	v_fmac_f32_e32 v19, v118, v54
	v_fmac_f32_e32 v22, v118, v58
	v_fmac_f32_e32 v12, v119, v27
	v_fmac_f32_e32 v13, v119, v31
	v_fmac_f32_e32 v14, v119, v35
	v_fmac_f32_e32 v15, v119, v39
	v_fmac_f32_e32 v16, v119, v43
	v_fmac_f32_e32 v17, v119, v47
	v_fmac_f32_e32 v18, v119, v51
	v_fmac_f32_e32 v19, v119, v55
	v_fmac_f32_e32 v22, v119, v59
	ds_read_b128 v[24:27], v21 offset:32
	ds_read_b128 v[28:31], v21 offset:4128
	ds_read_b128 v[32:35], v21 offset:8224
	ds_read_b128 v[36:39], v21 offset:12320
	ds_read_b128 v[40:43], v21 offset:16416
	ds_read_b128 v[44:47], v21 offset:20512
	ds_read_b128 v[48:51], v21 offset:24608
	ds_read_b128 v[52:55], v21 offset:28704
	ds_read_b128 v[56:59], v21 offset:32800
	s_waitcnt vmcnt(20) lgkmcnt(0)
	v_fmac_f32_e32 v12, v120, v24
	v_fmac_f32_e32 v13, v120, v28
	v_fmac_f32_e32 v14, v120, v32
	v_fmac_f32_e32 v15, v120, v36
	v_fmac_f32_e32 v16, v120, v40
	v_fmac_f32_e32 v17, v120, v44
	v_fmac_f32_e32 v18, v120, v48
	v_fmac_f32_e32 v19, v120, v52
	v_fmac_f32_e32 v22, v120, v56
	v_fmac_f32_e32 v12, v121, v25
	v_fmac_f32_e32 v13, v121, v29
	v_fmac_f32_e32 v14, v121, v33
	v_fmac_f32_e32 v15, v121, v37
	v_fmac_f32_e32 v16, v121, v41
	v_fmac_f32_e32 v17, v121, v45
	v_fmac_f32_e32 v18, v121, v49
	v_fmac_f32_e32 v19, v121, v53
	v_fmac_f32_e32 v22, v121, v57
	v_fmac_f32_e32 v12, v122, v26
	v_fmac_f32_e32 v13, v122, v30
	v_fmac_f32_e32 v14, v122, v34
	v_fmac_f32_e32 v15, v122, v38
	v_fmac_f32_e32 v16, v122, v42
	v_fmac_f32_e32 v17, v122, v46
	v_fmac_f32_e32 v18, v122, v50
	v_fmac_f32_e32 v19, v122, v54
	v_fmac_f32_e32 v22, v122, v58
	v_fmac_f32_e32 v12, v123, v27
	v_fmac_f32_e32 v13, v123, v31
	v_fmac_f32_e32 v14, v123, v35
	v_fmac_f32_e32 v15, v123, v39
	v_fmac_f32_e32 v16, v123, v43
	v_fmac_f32_e32 v17, v123, v47
	v_fmac_f32_e32 v18, v123, v51
	v_fmac_f32_e32 v19, v123, v55
	v_fmac_f32_e32 v22, v123, v59
	ds_read_b128 v[24:27], v21 offset:48
	ds_read_b128 v[28:31], v21 offset:4144
	ds_read_b128 v[32:35], v21 offset:8240
	ds_read_b128 v[36:39], v21 offset:12336
	ds_read_b128 v[40:43], v21 offset:16432
	ds_read_b128 v[44:47], v21 offset:20528
	ds_read_b128 v[48:51], v21 offset:24624
	ds_read_b128 v[52:55], v21 offset:28720
	ds_read_b128 v[56:59], v21 offset:32816
	s_waitcnt vmcnt(16) lgkmcnt(0)
	v_fmac_f32_e32 v12, v124, v24
	v_fmac_f32_e32 v13, v124, v28
	v_fmac_f32_e32 v14, v124, v32
	v_fmac_f32_e32 v15, v124, v36
	v_fmac_f32_e32 v16, v124, v40
	v_fmac_f32_e32 v17, v124, v44
	v_fmac_f32_e32 v18, v124, v48
	v_fmac_f32_e32 v19, v124, v52
	v_fmac_f32_e32 v22, v124, v56
	v_fmac_f32_e32 v12, v125, v25
	v_fmac_f32_e32 v13, v125, v29
	v_fmac_f32_e32 v14, v125, v33
	v_fmac_f32_e32 v15, v125, v37
	v_fmac_f32_e32 v16, v125, v41
	v_fmac_f32_e32 v17, v125, v45
	v_fmac_f32_e32 v18, v125, v49
	v_fmac_f32_e32 v19, v125, v53
	v_fmac_f32_e32 v22, v125, v57
	v_fmac_f32_e32 v12, v126, v26
	v_fmac_f32_e32 v13, v126, v30
	v_fmac_f32_e32 v14, v126, v34
	v_fmac_f32_e32 v15, v126, v38
	v_fmac_f32_e32 v16, v126, v42
	v_fmac_f32_e32 v17, v126, v46
	v_fmac_f32_e32 v18, v126, v50
	v_fmac_f32_e32 v19, v126, v54
	v_fmac_f32_e32 v22, v126, v58
	v_fmac_f32_e32 v12, v127, v27
	v_fmac_f32_e32 v13, v127, v31
	v_fmac_f32_e32 v14, v127, v35
	v_fmac_f32_e32 v15, v127, v39
	v_fmac_f32_e32 v16, v127, v43
	v_fmac_f32_e32 v17, v127, v47
	v_fmac_f32_e32 v18, v127, v51
	v_fmac_f32_e32 v19, v127, v55
	v_fmac_f32_e32 v22, v127, v59
	ds_read_b128 v[24:27], v21 offset:64
	ds_read_b128 v[28:31], v21 offset:4160
	ds_read_b128 v[32:35], v21 offset:8256
	ds_read_b128 v[36:39], v21 offset:12352
	ds_read_b128 v[40:43], v21 offset:16448
	ds_read_b128 v[44:47], v21 offset:20544
	ds_read_b128 v[48:51], v21 offset:24640
	ds_read_b128 v[52:55], v21 offset:28736
	ds_read_b128 v[56:59], v21 offset:32832
	s_waitcnt vmcnt(12) lgkmcnt(0)
	v_fmac_f32_e32 v12, v128, v24
	v_fmac_f32_e32 v13, v128, v28
	v_fmac_f32_e32 v14, v128, v32
	v_fmac_f32_e32 v15, v128, v36
	v_fmac_f32_e32 v16, v128, v40
	v_fmac_f32_e32 v17, v128, v44
	v_fmac_f32_e32 v18, v128, v48
	v_fmac_f32_e32 v19, v128, v52
	v_fmac_f32_e32 v22, v128, v56
	v_fmac_f32_e32 v12, v129, v25
	v_fmac_f32_e32 v13, v129, v29
	v_fmac_f32_e32 v14, v129, v33
	v_fmac_f32_e32 v15, v129, v37
	v_fmac_f32_e32 v16, v129, v41
	v_fmac_f32_e32 v17, v129, v45
	v_fmac_f32_e32 v18, v129, v49
	v_fmac_f32_e32 v19, v129, v53
	v_fmac_f32_e32 v22, v129, v57
	v_fmac_f32_e32 v12, v130, v26
	v_fmac_f32_e32 v13, v130, v30
	v_fmac_f32_e32 v14, v130, v34
	v_fmac_f32_e32 v15, v130, v38
	v_fmac_f32_e32 v16, v130, v42
	v_fmac_f32_e32 v17, v130, v46
	v_fmac_f32_e32 v18, v130, v50
	v_fmac_f32_e32 v19, v130, v54
	v_fmac_f32_e32 v22, v130, v58
	v_fmac_f32_e32 v12, v131, v27
	v_fmac_f32_e32 v13, v131, v31
	v_fmac_f32_e32 v14, v131, v35
	v_fmac_f32_e32 v15, v131, v39
	v_fmac_f32_e32 v16, v131, v43
	v_fmac_f32_e32 v17, v131, v47
	v_fmac_f32_e32 v18, v131, v51
	v_fmac_f32_e32 v19, v131, v55
	v_fmac_f32_e32 v22, v131, v59
	ds_read_b128 v[24:27], v21 offset:80
	ds_read_b128 v[28:31], v21 offset:4176
	ds_read_b128 v[32:35], v21 offset:8272
	ds_read_b128 v[36:39], v21 offset:12368
	ds_read_b128 v[40:43], v21 offset:16464
	ds_read_b128 v[44:47], v21 offset:20560
	ds_read_b128 v[48:51], v21 offset:24656
	ds_read_b128 v[52:55], v21 offset:28752
	ds_read_b128 v[56:59], v21 offset:32848
	s_waitcnt vmcnt(8) lgkmcnt(0)
	v_fmac_f32_e32 v12, v132, v24
	v_fmac_f32_e32 v13, v132, v28
	v_fmac_f32_e32 v14, v132, v32
	v_fmac_f32_e32 v15, v132, v36
	v_fmac_f32_e32 v16, v132, v40
	v_fmac_f32_e32 v17, v132, v44
	v_fmac_f32_e32 v18, v132, v48
	v_fmac_f32_e32 v19, v132, v52
	v_fmac_f32_e32 v22, v132, v56
	v_fmac_f32_e32 v12, v133, v25
	v_fmac_f32_e32 v13, v133, v29
	v_fmac_f32_e32 v14, v133, v33
	v_fmac_f32_e32 v15, v133, v37
	v_fmac_f32_e32 v16, v133, v41
	v_fmac_f32_e32 v17, v133, v45
	v_fmac_f32_e32 v18, v133, v49
	v_fmac_f32_e32 v19, v133, v53
	v_fmac_f32_e32 v22, v133, v57
	v_fmac_f32_e32 v12, v134, v26
	v_fmac_f32_e32 v13, v134, v30
	v_fmac_f32_e32 v14, v134, v34
	v_fmac_f32_e32 v15, v134, v38
	v_fmac_f32_e32 v16, v134, v42
	v_fmac_f32_e32 v17, v134, v46
	v_fmac_f32_e32 v18, v134, v50
	v_fmac_f32_e32 v19, v134, v54
	v_fmac_f32_e32 v22, v134, v58
	v_fmac_f32_e32 v12, v135, v27
	v_fmac_f32_e32 v13, v135, v31
	v_fmac_f32_e32 v14, v135, v35
	v_fmac_f32_e32 v15, v135, v39
	v_fmac_f32_e32 v16, v135, v43
	v_fmac_f32_e32 v17, v135, v47
	v_fmac_f32_e32 v18, v135, v51
	v_fmac_f32_e32 v19, v135, v55
	v_fmac_f32_e32 v22, v135, v59
	ds_read_b128 v[24:27], v21 offset:96
	ds_read_b128 v[28:31], v21 offset:4192
	ds_read_b128 v[32:35], v21 offset:8288
	ds_read_b128 v[36:39], v21 offset:12384
	ds_read_b128 v[40:43], v21 offset:16480
	ds_read_b128 v[44:47], v21 offset:20576
	ds_read_b128 v[48:51], v21 offset:24672
	ds_read_b128 v[52:55], v21 offset:28768
	ds_read_b128 v[56:59], v21 offset:32864
	s_waitcnt vmcnt(4) lgkmcnt(0)
	v_fmac_f32_e32 v12, v136, v24
	v_fmac_f32_e32 v13, v136, v28
	v_fmac_f32_e32 v14, v136, v32
	v_fmac_f32_e32 v15, v136, v36
	v_fmac_f32_e32 v16, v136, v40
	v_fmac_f32_e32 v17, v136, v44
	v_fmac_f32_e32 v18, v136, v48
	v_fmac_f32_e32 v19, v136, v52
	v_fmac_f32_e32 v22, v136, v56
	v_fmac_f32_e32 v12, v137, v25
	v_fmac_f32_e32 v13, v137, v29
	v_fmac_f32_e32 v14, v137, v33
	v_fmac_f32_e32 v15, v137, v37
	v_fmac_f32_e32 v16, v137, v41
	v_fmac_f32_e32 v17, v137, v45
	v_fmac_f32_e32 v18, v137, v49
	v_fmac_f32_e32 v19, v137, v53
	v_fmac_f32_e32 v22, v137, v57
	v_fmac_f32_e32 v12, v138, v26
	v_fmac_f32_e32 v13, v138, v30
	v_fmac_f32_e32 v14, v138, v34
	v_fmac_f32_e32 v15, v138, v38
	v_fmac_f32_e32 v16, v138, v42
	v_fmac_f32_e32 v17, v138, v46
	v_fmac_f32_e32 v18, v138, v50
	v_fmac_f32_e32 v19, v138, v54
	v_fmac_f32_e32 v22, v138, v58
	v_fmac_f32_e32 v12, v139, v27
	v_fmac_f32_e32 v13, v139, v31
	v_fmac_f32_e32 v14, v139, v35
	v_fmac_f32_e32 v15, v139, v39
	v_fmac_f32_e32 v16, v139, v43
	v_fmac_f32_e32 v17, v139, v47
	v_fmac_f32_e32 v18, v139, v51
	v_fmac_f32_e32 v19, v139, v55
	v_fmac_f32_e32 v22, v139, v59
	ds_read_b128 v[24:27], v21 offset:112
	ds_read_b128 v[28:31], v21 offset:4208
	ds_read_b128 v[32:35], v21 offset:8304
	ds_read_b128 v[36:39], v21 offset:12400
	ds_read_b128 v[40:43], v21 offset:16496
	ds_read_b128 v[44:47], v21 offset:20592
	ds_read_b128 v[48:51], v21 offset:24688
	ds_read_b128 v[52:55], v21 offset:28784
	ds_read_b128 v[56:59], v21 offset:32880
	s_waitcnt vmcnt(0) lgkmcnt(0)
	v_fmac_f32_e32 v12, v140, v24
	v_fmac_f32_e32 v13, v140, v28
	v_fmac_f32_e32 v14, v140, v32
	v_fmac_f32_e32 v15, v140, v36
	v_fmac_f32_e32 v16, v140, v40
	v_fmac_f32_e32 v17, v140, v44
	v_fmac_f32_e32 v18, v140, v48
	v_fmac_f32_e32 v19, v140, v52
	v_fmac_f32_e32 v22, v140, v56
	v_fmac_f32_e32 v12, v141, v25
	v_fmac_f32_e32 v13, v141, v29
	v_fmac_f32_e32 v14, v141, v33
	v_fmac_f32_e32 v15, v141, v37
	v_fmac_f32_e32 v16, v141, v41
	v_fmac_f32_e32 v17, v141, v45
	v_fmac_f32_e32 v18, v141, v49
	v_fmac_f32_e32 v19, v141, v53
	v_fmac_f32_e32 v22, v141, v57
	v_fmac_f32_e32 v12, v142, v26
	v_fmac_f32_e32 v13, v142, v30
	v_fmac_f32_e32 v14, v142, v34
	v_fmac_f32_e32 v15, v142, v38
	v_fmac_f32_e32 v16, v142, v42
	v_fmac_f32_e32 v17, v142, v46
	v_fmac_f32_e32 v18, v142, v50
	v_fmac_f32_e32 v19, v142, v54
	v_fmac_f32_e32 v22, v142, v58
	v_fmac_f32_e32 v12, v143, v27
	v_fmac_f32_e32 v13, v143, v31
	v_fmac_f32_e32 v14, v143, v35
	v_fmac_f32_e32 v15, v143, v39
	v_fmac_f32_e32 v16, v143, v43
	v_fmac_f32_e32 v17, v143, v47
	v_fmac_f32_e32 v18, v143, v51
	v_fmac_f32_e32 v19, v143, v55
	v_fmac_f32_e32 v22, v143, v59
	s_add_u32 s24, s24, 0x120000
	s_addc_u32 s25, s25, 0
	v_add_u32_e32 v21, 0x80, v21
	s_cmp_eq_u32 s24, 0x480000
	s_cbranch_scc0 .Lgemv_blk
	ds_write2st64_b32 v20, v12, v13 offset0:144 offset1:145
	ds_write2st64_b32 v20, v14, v15 offset0:146 offset1:147
	ds_write2st64_b32 v20, v16, v17 offset0:148 offset1:149
	ds_write2st64_b32 v20, v18, v19 offset0:150 offset1:151
	ds_write_b32 v20, v22 offset:38912
	s_waitcnt lgkmcnt(0)
	s_barrier
	s_and_saveexec_b64 s[24:25], vcc
	s_cbranch_execz .LBB0_50
	s_mul_i32 s0, s26, 0xffffff70
	s_add_i32 s0, s0, s37
	s_lshl_b32 s0, s0, 6
	s_ashr_i32 s1, s0, 31
	s_mul_i32 s28, s26, 0x9000
	s_mul_hi_i32 s27, s26, 0x9000
	s_add_u32 s28, s58, s28
	s_addc_u32 s27, s59, s27
	s_lshl_b64 s[0:1], s[0:1], 2
	s_add_u32 s28, s28, s0
	s_addc_u32 s29, s27, s1
	s_mul_hi_i32 s27, s26, 9
	s_mul_i32 s26, s26, 9
	v_lshl_add_u64 v[10:11], s[28:29], 0, v[4:5]
	v_lshl_add_u64 v[12:13], v[6:7], 0, s[0:1]
	s_mov_b64 s[28:29], 0
	v_mov_b32_e32 v14, v2
